# ATTN ping-pong, COMPUTE without s_nop pads: ring-advance scalars + second QK chain supply the 12 wait states, 3 exp2 per MFMA gap
# baseline (speedup 1.0000x reference)
.LBB0_954:
	s_add_i32 s5, s34, 1
	s_cmp_lg_u32 s34, 2
	s_cselect_b32 s34, s5, 0
	s_addk_i32 s31, 0xff00
	s_waitcnt vmcnt(3)
	s_add_i32 s15, s15, 1
	s_add_i32 s5, s30, s31
	s_add_i32 s33, s33, 64
	s_cmp_eq_u32 s5, 0
.Lpp_t2:
	s_cbranch_scc1 .LBB0_946
.LBB0_955:
	s_add_i32 s35, s15, -2
	s_lshl_b32 s5, s34, 13
	s_cmp_lt_u32 s15, s27
	s_cselect_b32 s10, s15, s29
	s_lshl_b64 s[6:7], s[10:11], 16
	s_waitcnt vmcnt(0)
	v_lshrrev_b32_e32 v3, v1, v138
	v_lshl_add_u64 v[6:7], v[116:117], 0, s[6:7]
	v_lshl_add_u64 v[8:9], v[118:119], 0, s[6:7]
	s_add_i32 s6, s5, 0xffffe000
	v_lshlrev_b32_e32 v3, 4, v3
	s_cmp_lg_u32 s34, 0
	v_and_b32_e32 v4, 0xf0f0f0f0, v3
	v_lshrrev_b32_e32 v3, v1, v139
	s_cselect_b32 s6, s6, 0x4000
	v_lshlrev_b32_e32 v3, 4, v3
	s_add_i32 s6, s6, 0
	v_and_b32_e32 v3, 0xf0f0f0f0, v3
	s_add_i32 s6, s20, s6
	s_waitcnt lgkmcnt(0)
	s_barrier
	s_add_i32 s7, s6, 0x6000
	s_mov_b32 m0, s6
	global_load_lds_dwordx4 v[6:7], off
	s_mov_b32 m0, s7
	global_load_lds_dwordx4 v[8:9], off
	s_add_i32 s6, s15, -1
	s_cmp_lt_u32 s35, 63
	s_cselect_b32 s10, s6, 63
	s_lshl_b64 s[6:7], s[10:11], 15
	v_lshl_add_u64 v[6:7], v[136:137], 0, s[6:7]
	global_load_dwordx2 v[138:139], v[6:7], off
	s_cmp_gt_u32 s35, s28
	s_cbranch_scc1 .Lpp_skip
	v_add_u32_e32 v149, s5, v140
	v_add_u32_e32 v150, s5, v141
	v_add_u32_sdwa v230, v4, s25 dst_sel:DWORD dst_unused:UNUSED_PAD src0_sel:BYTE_0 src1_sel:DWORD
	v_add_u32_sdwa v231, v4, s25 dst_sel:DWORD dst_unused:UNUSED_PAD src0_sel:BYTE_1 src1_sel:DWORD
	v_add_u32_sdwa v232, v4, s25 dst_sel:DWORD dst_unused:UNUSED_PAD src0_sel:BYTE_2 src1_sel:DWORD
	v_add_u32_sdwa v233, v4, s25 dst_sel:DWORD dst_unused:UNUSED_PAD src0_sel:BYTE_3 src1_sel:DWORD
	v_add_u32_sdwa v234, v3, s25 dst_sel:DWORD dst_unused:UNUSED_PAD src0_sel:BYTE_0 src1_sel:DWORD
	v_add_u32_sdwa v235, v3, s25 dst_sel:DWORD dst_unused:UNUSED_PAD src0_sel:BYTE_1 src1_sel:DWORD
	v_add_u32_sdwa v236, v3, s25 dst_sel:DWORD dst_unused:UNUSED_PAD src0_sel:BYTE_2 src1_sel:DWORD
	v_add_u32_sdwa v237, v3, s25 dst_sel:DWORD dst_unused:UNUSED_PAD src0_sel:BYTE_3 src1_sel:DWORD
	ds_read_b128 v[66:69], v230
	ds_read_b128 v[70:73], v231
	ds_read_b128 v[74:77], v232
	ds_read_b128 v[78:81], v233
	ds_read_b128 v[182:185], v149
	ds_read_b128 v[186:189], v149 offset:2048
	ds_read_b128 v[190:193], v149 offset:4096
	ds_read_b128 v[194:197], v149 offset:6144
	ds_read_b128 v[82:85], v234
	ds_read_b128 v[86:89], v235
	ds_read_b128 v[90:93], v236
	ds_read_b128 v[94:97], v237
	s_waitcnt lgkmcnt(8)
	ds_read_b128 v[198:201], v149 offset:512
	ds_read_b128 v[202:205], v149 offset:2560
	ds_read_b128 v[206:209], v149 offset:4608
	ds_read_b128 v[210:213], v149 offset:6656
	s_waitcnt lgkmcnt(8)
	ds_read_b64_tr_b16 v[152:153], v150
	ds_read_b64_tr_b16 v[154:155], v150 offset:512
	ds_read_b64_tr_b16 v[156:157], v150 offset:1024
	ds_read_b64_tr_b16 v[158:159], v150 offset:1536
	s_waitcnt lgkmcnt(8)
	ds_read_b64_tr_b16 v[160:161], v150 offset:2048
	ds_read_b64_tr_b16 v[162:163], v150 offset:2560
	ds_read_b64_tr_b16 v[164:165], v150 offset:3072
	ds_read_b64_tr_b16 v[166:167], v150 offset:3584
	s_waitcnt lgkmcnt(8)
	ds_read_b64_tr_b16 v[168:169], v150 offset:4096
	ds_read_b64_tr_b16 v[170:171], v150 offset:4608
	ds_read_b64_tr_b16 v[172:173], v150 offset:5120
	ds_read_b64_tr_b16 v[174:175], v150 offset:5632
	s_waitcnt lgkmcnt(8)
	ds_read_b64_tr_b16 v[214:215], v150 offset:6144
	ds_read_b64_tr_b16 v[216:217], v150 offset:6656
	ds_read_b64_tr_b16 v[218:219], v150 offset:7168
	ds_read_b64_tr_b16 v[220:221], v150 offset:7680
	s_waitcnt lgkmcnt(0)
	s_barrier
	v_mfma_f32_32x32x16_bf16 v[66:81], v[182:185], v[110:113], v[66:81]
	v_mfma_f32_32x32x16_bf16 v[66:81], v[186:189], v[98:101], v[66:81]
	v_mfma_f32_32x32x16_bf16 v[66:81], v[190:193], v[102:105], v[66:81]
	v_mfma_f32_32x32x16_bf16 v[66:81], v[194:197], v[106:109], v[66:81]
	s_cmp_lt_u32 s33, s14
	s_cbranch_scc0 .Lpp_bias
	v_mfma_f32_32x32x16_bf16 v[82:97], v[198:201], v[110:113], v[82:97]
	s_add_i32 s5, s34, 1
	s_cmp_lg_u32 s34, 2
	s_cselect_b32 s34, s5, 0
	v_mfma_f32_32x32x16_bf16 v[82:97], v[202:205], v[98:101], v[82:97]
	s_addk_i32 s31, 0xff00
	s_add_i32 s15, s15, 1
	s_add_i32 s5, s30, s31
	v_mfma_f32_32x32x16_bf16 v[82:97], v[206:209], v[102:105], v[82:97]
	s_add_i32 s33, s33, 64
	s_cmp_eq_u32 s5, 0
	v_exp_f32_e32 v66, v66
	v_exp_f32_e32 v67, v67
	v_exp_f32_e32 v68, v68
	v_mfma_f32_32x32x16_bf16 v[82:97], v[210:213], v[106:109], v[82:97]
	v_exp_f32_e32 v69, v69
	v_exp_f32_e32 v70, v70
	v_exp_f32_e32 v71, v71
	v_exp_f32_e32 v72, v72
	v_exp_f32_e32 v73, v73
	v_cvt_pk_bf16_f32 v4, v66, v67
	v_cvt_pk_bf16_f32 v5, v68, v69
	v_cvt_pk_bf16_f32 v6, v70, v71
	v_cvt_pk_bf16_f32 v7, v72, v73
	v_exp_f32_e32 v74, v74
	v_exp_f32_e32 v75, v75
	v_mfma_f32_32x32x16_bf16 v[34:49], v[4:7], v[152:155], v[34:49]
	v_exp_f32_e32 v76, v76
	v_exp_f32_e32 v77, v77
	v_exp_f32_e32 v78, v78
	v_mfma_f32_32x32x16_bf16 v[18:33], v[4:7], v[168:171], v[18:33]
	v_exp_f32_e32 v79, v79
	v_exp_f32_e32 v80, v80
	v_exp_f32_e32 v81, v81
	v_mfma_f32_32x32x16_bf16 v[50:65], v[4:7], v[226:229], v[50:65]
	v_cvt_pk_bf16_f32 v8, v74, v75
	v_cvt_pk_bf16_f32 v9, v76, v77
	v_cvt_pk_bf16_f32 v10, v78, v79
	v_cvt_pk_bf16_f32 v11, v80, v81
	v_exp_f32_e32 v82, v82
	v_exp_f32_e32 v83, v83
	v_mfma_f32_32x32x16_bf16 v[34:49], v[8:11], v[156:159], v[34:49]
	v_exp_f32_e32 v84, v84
	v_exp_f32_e32 v85, v85
	v_exp_f32_e32 v86, v86
	v_mfma_f32_32x32x16_bf16 v[18:33], v[8:11], v[172:175], v[18:33]
	v_exp_f32_e32 v87, v87
	v_exp_f32_e32 v88, v88
	v_exp_f32_e32 v89, v89
	v_mfma_f32_32x32x16_bf16 v[50:65], v[8:11], v[226:229], v[50:65]
	v_cvt_pk_bf16_f32 v12, v82, v83
	v_cvt_pk_bf16_f32 v13, v84, v85
	v_cvt_pk_bf16_f32 v14, v86, v87
	v_cvt_pk_bf16_f32 v15, v88, v89
	v_exp_f32_e32 v90, v90
	v_exp_f32_e32 v91, v91
	v_mfma_f32_32x32x16_bf16 v[34:49], v[12:15], v[160:163], v[34:49]
	v_exp_f32_e32 v92, v92
	v_exp_f32_e32 v93, v93
	v_exp_f32_e32 v94, v94
	v_mfma_f32_32x32x16_bf16 v[18:33], v[12:15], v[214:217], v[18:33]
	v_exp_f32_e32 v95, v95
	v_exp_f32_e32 v96, v96
	v_exp_f32_e32 v97, v97
	v_mfma_f32_32x32x16_bf16 v[50:65], v[12:15], v[226:229], v[50:65]
	v_cvt_pk_bf16_f32 v222, v90, v91
	v_cvt_pk_bf16_f32 v223, v92, v93
	v_cvt_pk_bf16_f32 v224, v94, v95
	v_cvt_pk_bf16_f32 v225, v96, v97
	s_nop 1
	v_mfma_f32_32x32x16_bf16 v[34:49], v[222:225], v[164:167], v[34:49]
	v_mfma_f32_32x32x16_bf16 v[18:33], v[222:225], v[218:221], v[18:33]
	v_mfma_f32_32x32x16_bf16 v[50:65], v[222:225], v[226:229], v[50:65]
	s_branch .Lpp_t2
